# attention softmax: packed v_pk_fma_f32 split into two v_fma_f32 (bit-identical)
# baseline (speedup 1.0000x reference)
; template <int kind>
; __device__ void attn_job(const Params& p, int layer, int idx, char* smem) {
;     ...
;   auto tile_row0 = [&](int i) { return (i < 4) ? (NLAT + b * CTXL + i * 64) : (lat0 + (i - 4) * 64); };
;   u32x4 kreg, vreg;
;   {
;     const size_t ro = (size_t)(tile_row0(0) + lkey) * ZW;
;     kreg = *(const u32x4*)(Z + ro + kcol + lc * 8);
;     vreg = *(const u32x4*)(Z + ro + vcol + lc * 8);
;   }
;   for (int i = 0; i < ntiles; ++i) {
;     u16* Kb = Ks + (i & 1) * 64 * KS_STRIDE;
;     u16* Vb = Vt + (i & 1) * 64 * KS_STRIDE;
;     *(u32x4*)(Kb + lkey * KS_STRIDE + lc * 8) = kreg;
;     *(u32x4*)(Vb + lkey * KS_STRIDE + lc * 8) = vreg;
;     lds_barrier();
;     if (i + 1 < ntiles) {
;       const size_t ro = (size_t)(tile_row0(i + 1) + lkey) * ZW;
;       kreg = *(const u32x4*)(Z + ro + kcol + lc * 8);
;       vreg = *(const u32x4*)(Z + ro + vcol + lc * 8);
;     }
;     if (kind == 1 && i >= 4) {
;       const int kr = R0 + i - 4;
;       if (kr >= r0A && kr < r0A + 9) {
;         f32x16 s[2];
; #pragma unroll
;         for (int st = 0; st < 4; ++st) s[0] = mfma32(ld_frag16(Kb + (k0 + tq) * KS_STRIDE + 16 * st + 8 * hh), qf[st], st == 0 ? zero16 : s[0]);
;         const bool rowvalid = (kr >= r0l) && (kr < r0l + 8);
;         const unsigned m = rowvalid ? colmask : 0u;
;         const float* brow = rpbs + (kr - qrow_l + 7) * 32 + dcbase;
; #pragma unroll
;         for (int e = 0; e < 16; ++e) {
; __device__ void mixer_phase(const Params& p, int layer, char* smem) {
;     ...
;   for (;;) {
;     if (threadIdx.x == 0) *slot = atomicAdd(ctr, 1u);
;     __syncthreads();
;     int job = (int)*slot;
;     __syncthreads();
;     if (job >= njobs) break;
;     if (job >= 256 && job < 320) {
;       bias_job(p, layer, job - 256, smem);
;       continue;
;     }
;     if (job >= 320) job -= 64;
;     if (job < 256) {
;       for (int rep = 0; rep < REP_CHAIN; ++rep) {
;         if (job < 128) hgrn_chain(p, layer, job, smem);
;         else mlstm_chain(p, layer, job - 128, smem);
;         __syncthreads();
;       }
;     } else {
;       for (int rep = 0; rep < REP_ATT; ++rep) {
;         if (job < 768) attn_job<0>(p, layer, job - 256, smem);
;         else if (job < 1280) attn_job<1>(p, layer, job - 768, smem);
;         else if (job < 1344) attn_job<2>(p, layer, job - 1280, smem);
;         else attn_job<3>(p, layer, job - 1344, smem);
.LBB0_437:
	s_or_b64 exec, exec, s[0:1]
	v_mov_b32_e32 v0, s19
	s_waitcnt lgkmcnt(0)
	s_barrier
	ds_read_b32 v0, v0
	s_mov_b64 s[0:1], -1
	s_waitcnt lgkmcnt(0)
	s_barrier
	v_cmp_le_i32_e32 vcc, s27, v0
	v_readfirstlane_b32 s30, v0
	s_cbranch_vccnz .LBB0_432
	s_and_b32 s0, s30, 0xffffffc0
	s_cmpk_lg_i32 s0, 0x100
	s_mov_b64 s[0:1], -1
	s_cbranch_scc0 .LBB0_762
	s_sub_i32 s0, s30, 64
	s_cmpk_gt_i32 s30, 0x13f
	s_cselect_b32 s18, s0, s30
	s_cmpk_lt_i32 s18, 0x100
	s_mov_b64 s[0:1], -1
	s_cbranch_scc1 .LBB0_530
	v_sub_co_u32_e32 v0, vcc, s18, v251
	s_nop 0
	v_readfirstlane_b32 s6, v0
	s_andn2_b64 vcc, exec, vcc
	s_cbranch_vccz .LBB0_518
	s_cmpk_gt_u32 s18, 0x4ff
	s_cbranch_scc0 .LBB0_456
	s_cmpk_gt_u32 s18, 0x53f
	s_cbranch_scc0 .LBB0_452
	s_lshl_b32 s0, s18, 6
	v_mov_b32_e32 v20, v234
	s_and_b32 s2, s0, 0xf00
	s_and_b32 s3, s0, 0xc0
	v_mov_b64_e32 v[82:83], s[80:81]
	v_readfirstlane_b32 s0, v20
	v_and_b32_e32 v159, 31, v20
	s_ashr_i32 s0, s0, 1
	s_andn2_b32 s0, s0, 31
	v_or_b32_e32 v0, s2, v159
	v_add_u32_e32 v0, s0, v0
	s_waitcnt vmcnt(4)
	v_add_u32_e32 v140, 0x8000, v0
	v_readlane_b32 s8, v254, 34
	v_mad_i64_i32 v[2:3], s[0:1], v140, s79, v[82:83]
	v_readlane_b32 s9, v254, 35
	v_bfe_u32 v183, v20, 5, 1
	s_lshl_b32 s0, s3, 1
	s_mov_b32 s1, s9
	v_lshl_add_u64 v[2:3], v[2:3], 0, s[0:1]
	v_lshlrev_b32_e32 v26, 4, v183
	v_mov_b32_e32 v27, v1
	v_lshl_add_u64 v[2:3], v[2:3], 0, v[26:27]
	s_mov_b64 s[10:11], 0x1600
	s_movk_i32 s1, 0x1000
	v_lshl_add_u64 v[4:5], v[2:3], 0, s[10:11]
	v_add_co_u32_e32 v2, vcc, s1, v2
	v_mov_b32_e32 v6, v1
	s_nop 0
	v_addc_co_u32_e32 v3, vcc, 0, v3, vcc
	global_load_dwordx4 v[96:99], v[2:3], off offset:1536
	global_load_dwordx4 v[92:95], v[4:5], off offset:32
	global_load_dwordx4 v[88:91], v[4:5], off offset:64
	global_load_dwordx4 v[84:87], v[4:5], off offset:96
	v_mov_b32_e32 v2, v1
	v_mov_b32_e32 v3, v1
	v_mov_b32_e32 v4, v1
	v_mov_b32_e32 v5, v1
	v_mov_b32_e32 v7, v1
	v_mov_b32_e32 v8, v1
	v_mov_b32_e32 v9, v1
	v_mov_b32_e32 v10, v1
	v_mov_b32_e32 v11, v1
	v_mov_b32_e32 v12, v1
	v_mov_b32_e32 v13, v1
	v_mov_b32_e32 v14, v1
	v_mov_b32_e32 v15, v1
	v_mov_b32_e32 v0, v1
	v_mov_b64_e32 v[16:17], v[14:15]
	v_and_b32_e32 v18, 16, v20
	v_lshlrev_b32_e32 v19, 2, v20
	v_mov_b64_e32 v[14:15], v[12:13]
	v_mov_b64_e32 v[12:13], v[10:11]
	v_mov_b64_e32 v[10:11], v[8:9]
	v_mov_b64_e32 v[8:9], v[6:7]
	v_mov_b64_e32 v[6:7], v[4:5]
	v_mov_b64_e32 v[4:5], v[2:3]
	v_mov_b64_e32 v[2:3], v[0:1]
	v_ashrrev_i32_e32 v27, 3, v20
	v_bfe_u32 v0, v20, 2, 2
	v_and_or_b32 v18, v19, 12, v18
	v_lshl_or_b32 v0, v183, 2, v0
	v_lshlrev_b32_e32 v18, 1, v18
	s_movk_i32 s1, 0x90
	v_add_u32_e32 v109, s2, v27
	s_or_b32 s4, s3, 0xc00
	v_mad_u32_u24 v108, v0, s1, v18
	v_add_u32_e32 v218, 0x8000, v109
	v_lshlrev_b32_e32 v0, 3, v20
	s_or_b32 s5, s3, 0xd00
	v_mad_i64_i32 v[22:23], s[2:3], v218, s79, v[82:83]
	s_lshl_b32 s8, s4, 1
	v_and_b32_e32 v0, 56, v0
	v_lshl_add_u64 v[18:19], v[22:23], 0, s[8:9]
	v_lshlrev_b32_e32 v0, 1, v0
	s_lshl_b32 s2, s5, 1
	s_mov_b32 s3, s9
	v_lshl_add_u64 v[18:19], v[18:19], 0, v[0:1]
	v_lshl_add_u64 v[22:23], v[22:23], 0, s[2:3]
	global_load_dwordx4 v[18:21], v[18:19], off
	v_lshl_add_u64 v[22:23], v[22:23], 0, v[0:1]
	global_load_dwordx4 v[22:25], v[22:23], off
	v_mul_lo_u32 v27, v27, s1
	v_add3_u32 v141, 0, v27, v0
	s_waitcnt vmcnt(1)
	ds_write_b128 v141, v[18:21]
	s_waitcnt vmcnt(0)
	ds_write_b128 v141, v[22:25] offset:18432
	v_add_u32_e32 v18, 0x8040, v109
	v_mad_i64_i32 v[18:19], s[4:5], v18, s79, v[82:83]
	v_lshl_add_u64 v[20:21], v[18:19], 0, s[8:9]
	v_lshl_add_u64 v[18:19], v[18:19], 0, s[2:3]
	s_waitcnt lgkmcnt(0)
	s_barrier
	v_lshl_add_u64 v[20:21], v[20:21], 0, v[0:1]
	v_lshl_add_u64 v[18:19], v[18:19], 0, v[0:1]
	global_load_dwordx4 v[100:103], v[20:21], off
	global_load_dwordx4 v[104:107], v[18:19], off
	s_setprio 1
	v_add_u32_e32 v219, 0, v26
	v_mad_u32_u24 v138, v159, s1, v219
	ds_read_b128 v[34:37], v138
	ds_read_b128 v[38:41], v138 offset:32
	s_waitcnt lgkmcnt(1)
	v_mfma_f32_32x32x16_bf16 v[18:33], v[34:37], v[96:99], v[2:17]
	ds_read_b128 v[34:37], v138 offset:64
	s_waitcnt lgkmcnt(1)
	v_mfma_f32_32x32x16_bf16 v[18:33], v[38:41], v[92:95], v[18:33]
	s_waitcnt lgkmcnt(0)
	v_mfma_f32_32x32x16_bf16 v[18:33], v[34:37], v[88:91], v[18:33]
	ds_read_b128 v[34:37], v138 offset:96
	s_waitcnt lgkmcnt(0)
	v_mfma_f32_32x32x16_bf16 v[18:33], v[34:37], v[84:87], v[18:33]
	ds_read_b128 v[34:37], v138 offset:4608
	s_waitcnt lgkmcnt(0)
	v_mfma_f32_32x32x16_bf16 v[66:81], v[34:37], v[96:99], v[2:17]
	ds_read_b128 v[34:37], v138 offset:4640
	s_waitcnt lgkmcnt(0)
	v_mfma_f32_32x32x16_bf16 v[66:81], v[34:37], v[92:95], v[66:81]
	ds_read_b128 v[34:37], v138 offset:4672
	s_waitcnt lgkmcnt(0)
	v_mfma_f32_32x32x16_bf16 v[66:81], v[34:37], v[88:91], v[66:81]
	ds_read_b128 v[34:37], v138 offset:4704
	s_waitcnt lgkmcnt(0)
; DI f32x16 mfma32(bf16x8 a, bf16x8 b, f32x16 c) { return __builtin_amdgcn_mfma_f32_32x32x16_bf16(a, b, c, 0, 0, 0); }
; template <int NB>
; DI void softmax_pv(f32x16 (&s)[2], float& mrun, float& lsum, f32x16 (&O)[2], unsigned vaddr) {
;   u32x2 vf[16];
;   u32x2 vf8[8];
;   if (NB == 2) tr_read_vtile(vf, vaddr);
;   else tr_read_vtile8(vf8, vaddr);
;   float mx = -1e30f;
; #pragma unroll
;   for (int kb = 0; kb < NB; ++kb)
; #pragma unroll
;     for (int e = 0; e < 16; ++e) mx = fmaxf(mx, s[kb][e]);
;   mx = xmax32(mx);
;   constexpr float THR = 8.f;
;   float alpha = 1.f;
;   if (__builtin_amdgcn_ballot_w64(mx - mrun > THR) != 0ull) {
;     const float mnew = fmaxf(mrun, mx);
;     alpha = __builtin_amdgcn_exp2f((mrun - mnew) * L2E);
;     mrun = mnew;
; #pragma unroll
;     for (int e = 0; e < 16; ++e) { O[0][e] *= alpha; O[1][e] *= alpha; }
;   }
;   typedef float f32x2 __attribute__((ext_vector_type(2)));
;   const float mb = mrun * L2E;
;   f32x2 ps2 = {0.f, 0.f};
;   const f32x2 l2e2 = {L2E, L2E}, mb2 = {mb, mb};
;   if (NB == 2) {
; #pragma unroll
;     for (int kb = 0; kb < 2; ++kb) {
; #pragma unroll
;       for (int e = 0; e < 16; e += 2) {
;         f32x2 t = {s[kb][e], s[kb][e + 1]};
;         t = t * l2e2 - mb2;
;         f32x2 pv;
;         pv[0] = __builtin_amdgcn_exp2f(t[0]);
;         pv[1] = __builtin_amdgcn_exp2f(t[1]);
;         s[kb][e] = pv[0];
;         s[kb][e + 1] = pv[1];
;         ps2 += pv;
;       }
;       u32x4 pp[2];
; #pragma unroll
;       for (int st = 0; st < 2; ++st)
; #pragma unroll
;         for (int j = 0; j < 4; ++j) pp[st][j] = pk_bf16(s[kb][8 * st + 2 * j], s[kb][8 * st + 2 * j + 1]);
;       __builtin_amdgcn_sched_barrier(0);
;       __builtin_amdgcn_s_setprio(1);
; #pragma unroll
;       for (int st = 0; st < 2; ++st) {
;         const bf16x8 pf = as_bf16x8(pp[st]);
; #pragma unroll
;         for (int db = 0; db < 2; ++db) {
;           const int ix = ((kb * 2 + st) * 2 + db) * 2;
;           u32x4 av;
;           av[0] = vf[ix][0]; av[1] = vf[ix][1]; av[2] = vf[ix + 1][0]; av[3] = vf[ix + 1][1];
;           O[db] = mfma32(as_bf16x8(av), pf, O[db]);
;         }
;       }
;       __builtin_amdgcn_s_setprio(0);
;       __builtin_amdgcn_sched_barrier(0);
;     }
	v_mfma_f32_32x32x16_bf16 v[66:81], v[34:37], v[84:87], v[66:81]
	s_setprio 0
	v_max3_f32 v34, v18, s24, v19
	v_max3_f32 v34, v34, v20, v21
	v_max3_f32 v34, v34, v22, v23
	v_max3_f32 v34, v34, v24, v25
	v_max3_f32 v34, v34, v26, v27
	v_max3_f32 v34, v34, v28, v29
	v_max3_f32 v34, v34, v30, v31
	v_max3_f32 v34, v34, v32, v33
	s_nop 2
	v_max3_f32 v34, v34, v66, v67
	v_max3_f32 v34, v34, v68, v69
	v_max3_f32 v34, v34, v70, v71
	v_max3_f32 v34, v34, v72, v73
	v_max3_f32 v34, v34, v74, v75
	v_max3_f32 v34, v34, v76, v77
	v_max3_f32 v34, v34, v78, v79
	v_max3_f32 v34, v34, v80, v81
	v_mov_b32_e32 v35, v34
	s_nop 1
	v_permlane32_swap_b32_e32 v34, v35
	v_max_f32_e32 v35, v35, v35
	v_max_f32_e32 v34, v34, v34
	v_max_f32_e32 v34, v34, v35
	s_add_i32 s1, 0, 0x4800
	v_max_f32_e32 v35, 0xf149f2ca, v34
	v_add_f32_e32 v34, 0x7149f2ca, v34
	s_cmp_lg_u32 s1, -1
	v_cmp_lt_f32_e32 vcc, s25, v34
	s_cselect_b32 s1, s1, 0
	s_cmp_eq_u64 vcc, 0
	s_cselect_b64 vcc, -1, 0
	v_cndmask_b32_e32 v185, v35, v240, vcc
	v_mul_f32_e32 v158, 0x3fb8aa3b, v185
	v_fma_f32 v18, v18, s28, -v158
	v_fma_f32 v19, v19, s28, -v158
	v_sub_f32_e32 v36, 0xf149f2ca, v35
	v_exp_f32_e32 v142, v18
	v_exp_f32_e32 v143, v19
	v_fma_f32 v18, v20, s28, -v158
	v_fma_f32 v19, v21, s28, -v158
	v_mul_f32_e32 v36, 0x3fb8aa3b, v36
	v_exp_f32_e32 v144, v18
	v_exp_f32_e32 v145, v19
	v_fma_f32 v18, v22, s28, -v158
	v_fma_f32 v19, v23, s28, -v158
	v_exp_f32_e32 v36, v36
	v_exp_f32_e32 v146, v18
	v_exp_f32_e32 v147, v19
	v_fma_f32 v18, v24, s28, -v158
	v_fma_f32 v19, v25, s28, -v158
	v_add_u32_e32 v220, s1, v108
	v_exp_f32_e32 v148, v18
	v_exp_f32_e32 v149, v19
	v_fma_f32 v18, v26, s28, -v158
	v_fma_f32 v19, v27, s28, -v158
	ds_read_b64_tr_b16 v[160:161], v220 offset:0
	ds_read_b64_tr_b16 v[162:163], v220 offset:1152
	ds_read_b64_tr_b16 v[134:135], v220 offset:64
	ds_read_b64_tr_b16 v[136:137], v220 offset:1216
	ds_read_b64_tr_b16 v[130:131], v220 offset:2304
	ds_read_b64_tr_b16 v[132:133], v220 offset:3456
	ds_read_b64_tr_b16 v[126:127], v220 offset:2368
	ds_read_b64_tr_b16 v[128:129], v220 offset:3520
	ds_read_b64_tr_b16 v[122:123], v220 offset:4608
	ds_read_b64_tr_b16 v[124:125], v220 offset:5760
	ds_read_b64_tr_b16 v[118:119], v220 offset:4672
	ds_read_b64_tr_b16 v[120:121], v220 offset:5824
	ds_read_b64_tr_b16 v[114:115], v220 offset:6912
	ds_read_b64_tr_b16 v[116:117], v220 offset:8064
	ds_read_b64_tr_b16 v[110:111], v220 offset:6976
	ds_read_b64_tr_b16 v[112:113], v220 offset:8128
	s_waitcnt lgkmcnt(0)
	v_mul_f32_e32 v34, 0, v36
	v_exp_f32_e32 v150, v18
	v_exp_f32_e32 v151, v19
	v_fma_f32 v18, v28, s28, -v158
	v_fma_f32 v19, v29, s28, -v158
	v_cndmask_b32_e64 v50, v34, 0, vcc
	v_exp_f32_e32 v152, v18
	v_exp_f32_e32 v153, v19
	v_fma_f32 v18, v30, s28, -v158
	v_fma_f32 v19, v31, s28, -v158
	v_mov_b32_e32 v51, v50
	v_exp_f32_e32 v154, v18
	v_exp_f32_e32 v155, v19
	v_fma_f32 v18, v32, s28, -v158
	v_fma_f32 v19, v33, s28, -v158
	v_mov_b32_e32 v52, v50
	v_exp_f32_e32 v156, v18
	v_exp_f32_e32 v157, v19
	v_mov_b32_e32 v53, v50
	v_mov_b32_e32 v54, v50
	v_mov_b32_e32 v55, v50
	v_mov_b32_e32 v56, v50
	v_mov_b32_e32 v57, v50
	v_mov_b32_e32 v58, v50
	v_mov_b32_e32 v59, v50
	v_mov_b32_e32 v60, v50
	v_mov_b32_e32 v61, v50
	v_mov_b32_e32 v62, v50
	v_mov_b32_e32 v63, v50
	v_mov_b32_e32 v64, v50
	v_mov_b32_e32 v65, v50
	v_cvt_pk_bf16_f32 v164, v142, v143
	v_cvt_pk_bf16_f32 v165, v144, v145
	v_cvt_pk_bf16_f32 v166, v146, v147
	v_cvt_pk_bf16_f32 v167, v148, v149
	v_cvt_pk_bf16_f32 v168, v150, v151
	v_cvt_pk_bf16_f32 v169, v152, v153
	v_cvt_pk_bf16_f32 v170, v154, v155
	v_cvt_pk_bf16_f32 v171, v156, v157
	s_setprio 1
	v_mov_b64_e32 v[18:19], v[50:51]
	v_mov_b64_e32 v[20:21], v[52:53]
	v_mov_b64_e32 v[22:23], v[54:55]
	v_mov_b64_e32 v[24:25], v[56:57]
	v_mov_b64_e32 v[26:27], v[58:59]
	v_mov_b64_e32 v[28:29], v[60:61]
	v_mov_b64_e32 v[30:31], v[62:63]
	v_mov_b64_e32 v[32:33], v[64:65]
	v_mfma_f32_32x32x16_bf16 v[34:49], v[160:163], v[164:167], v[50:65]
	s_nop 0
	v_mfma_f32_32x32x16_bf16 v[18:33], v[134:137], v[164:167], v[18:33]
	v_mfma_f32_32x32x16_bf16 v[34:49], v[130:133], v[168:171], v[34:49]
	v_mfma_f32_32x32x16_bf16 v[18:33], v[126:129], v[168:171], v[18:33]
	s_setprio 0
	s_nop 1
	v_fma_f32 v52, v66, s28, -v158
	v_fma_f32 v53, v67, s28, -v158
	v_exp_f32_e32 v160, v52
	v_exp_f32_e32 v161, v53
	v_fma_f32 v52, v68, s28, -v158
	v_fma_f32 v53, v69, s28, -v158
	s_nop 0
	v_exp_f32_e32 v162, v52
	v_exp_f32_e32 v163, v53
	v_fma_f32 v52, v70, s28, -v158
	v_fma_f32 v53, v71, s28, -v158
	s_nop 0
	v_exp_f32_e32 v164, v52
	v_exp_f32_e32 v165, v53
	v_fma_f32 v52, v72, s28, -v158
	v_fma_f32 v53, v73, s28, -v158
	v_cvt_pk_bf16_f32 v54, v164, v165
	v_exp_f32_e32 v166, v52
	v_exp_f32_e32 v167, v53
	v_fma_f32 v52, v74, s28, -v158
	v_fma_f32 v53, v75, s28, -v158
	v_cvt_pk_bf16_f32 v55, v166, v167
	v_exp_f32_e32 v168, v52
	v_exp_f32_e32 v169, v53
	v_fma_f32 v52, v76, s28, -v158
	v_fma_f32 v53, v77, s28, -v158
	v_cvt_pk_bf16_f32 v56, v168, v169
	v_exp_f32_e32 v170, v52
	v_exp_f32_e32 v171, v53
	v_fma_f32 v52, v78, s28, -v158
	v_fma_f32 v53, v79, s28, -v158
	v_cvt_pk_bf16_f32 v57, v170, v171
	v_exp_f32_e32 v178, v52
	v_exp_f32_e32 v179, v53
	v_fma_f32 v52, v80, s28, -v158
	v_fma_f32 v53, v81, s28, -v158
	v_cvt_pk_bf16_f32 v58, v178, v179
	v_exp_f32_e32 v180, v52
	v_exp_f32_e32 v181, v53
	v_cvt_pk_bf16_f32 v52, v160, v161
	v_cvt_pk_bf16_f32 v53, v162, v163
	v_cvt_pk_bf16_f32 v59, v180, v181
	s_setprio 1
	v_mfma_f32_32x32x16_bf16 v[34:49], v[122:125], v[52:55], v[34:49]
	v_mfma_f32_32x32x16_bf16 v[18:33], v[118:121], v[52:55], v[18:33]
	v_mfma_f32_32x32x16_bf16 v[34:49], v[114:117], v[56:59], v[34:49]
	v_mfma_f32_32x32x16_bf16 v[18:33], v[110:113], v[56:59], v[18:33]
	s_setprio 0
	v_add_u32_e32 v51, 0x8080, v109
	v_mad_i64_i32 v[52:53], s[4:5], v51, s79, v[82:83]
	s_waitcnt vmcnt(1)
	ds_write_b128 v141, v[100:103] offset:9216
	s_waitcnt vmcnt(0)
	ds_write_b128 v141, v[104:107] offset:27648
	v_writelane_b32 v254, s8, 34
	s_waitcnt lgkmcnt(0)
	s_barrier
; template <int NB>
; DI void softmax_pv(f32x16 (&s)[2], float& mrun, float& lsum, f32x16 (&O)[2], unsigned vaddr) {
;     ...
;   float mx = -1e30f;
; #pragma unroll
;   for (int kb = 0; kb < NB; ++kb)
; #pragma unroll
;     for (int e = 0; e < 16; ++e) mx = fmaxf(mx, s[kb][e]);
;   mx = xmax32(mx);
;   constexpr float THR = 8.f;
;   float alpha = 1.f;
;   if (__builtin_amdgcn_ballot_w64(mx - mrun > THR) != 0ull) {
;     const float mnew = fmaxf(mrun, mx);
;     alpha = __builtin_amdgcn_exp2f((mrun - mnew) * L2E);
;     mrun = mnew;
; #pragma unroll
; template <int kind>
; __device__ void attn_job(const Params& p, int layer, int idx, char* smem) {
;     ...
;   for (int i = 0; i < ntiles; ++i) {
;     u16* Kb = Ks + (i & 1) * 64 * KS_STRIDE;
;     u16* Vb = Vt + (i & 1) * 64 * KS_STRIDE;
;     *(u32x4*)(Kb + lkey * KS_STRIDE + lc * 8) = kreg;
;     *(u32x4*)(Vb + lkey * KS_STRIDE + lc * 8) = vreg;
;     lds_barrier();
;     if (i + 1 < ntiles) {
;       const size_t ro = (size_t)(tile_row0(i + 1) + lkey) * ZW;
;       kreg = *(const u32x4*)(Z + ro + kcol + lc * 8);
;       vreg = *(const u32x4*)(Z + ro + vcol + lc * 8);
;     }
;     if (kind == 1 && i >= 4) {
;       const int kr = R0 + i - 4;
;       if (kr >= r0A && kr < r0A + 9) {
;         f32x16 s[2];
; #pragma unroll
;         for (int st = 0; st < 4; ++st) s[0] = mfma32(ld_frag16(Kb + (k0 + tq) * KS_STRIDE + 16 * st + 8 * hh), qf[st], st == 0 ? zero16 : s[0]);
;         const bool rowvalid = (kr >= r0l) && (kr < r0l + 8);
;         const unsigned m = rowvalid ? colmask : 0u;
;         const float* brow = rpbs + (kr - qrow_l + 7) * 32 + dcbase;
; #pragma unroll
;         for (int e = 0; e < 16; ++e) {
;           const float bias = brow[(e & 3) + 8 * (e >> 2)];
;           s[0][e] = ((m >> e) & 1u) ? s[0][e] + bias : -1e30f;
;         }
;         softmax_pv<1>(s, mrun, lsum, O, (unsigned)(size_t)Vb + vlane_off + (unsigned)(k0 * KS_STRIDE * 2));
;       }
;     } else {
;       f32x16 s[2];
;       __builtin_amdgcn_s_setprio(1);
; #pragma unroll
;       for (int kb = 0; kb < 2; ++kb) {
; #pragma unroll
;         for (int st = 0; st < 4; ++st) s[kb] = mfma32(ld_frag16(Kb + (kb * 32 + tq) * KS_STRIDE + 16 * st + 8 * hh), qf[st], st == 0 ? zero16 : s[kb]);
;       }
;       __builtin_amdgcn_s_setprio(0);
;       softmax_pv<2>(s, mrun, lsum, O, (unsigned)(size_t)Vb + vlane_off);
	s_nop 0
	v_lshl_add_u64 v[54:55], v[52:53], 0, s[8:9]
	v_lshl_add_u64 v[54:55], v[54:55], 0, v[0:1]
	v_lshl_add_u64 v[52:53], v[52:53], 0, s[2:3]
	v_lshl_add_u64 v[52:53], v[52:53], 0, v[0:1]
	global_load_dwordx4 v[100:103], v[54:55], off
	global_load_dwordx4 v[104:107], v[52:53], off
	v_writelane_b32 v254, s9, 35
	s_setprio 1
	ds_read_b128 v[52:55], v138 offset:9216
	ds_read_b128 v[56:59], v138 offset:9248
	s_waitcnt lgkmcnt(1)
	v_mfma_f32_32x32x16_bf16 v[68:83], v[52:55], v[96:99], v[2:17]
	ds_read_b128 v[52:55], v138 offset:9280
	ds_read_b128 v[110:113], v138 offset:13824
	s_waitcnt lgkmcnt(2)
	v_mfma_f32_32x32x16_bf16 v[68:83], v[56:59], v[92:95], v[68:83]
	s_waitcnt lgkmcnt(1)
	v_mfma_f32_32x32x16_bf16 v[68:83], v[52:55], v[88:91], v[68:83]
	ds_read_b128 v[52:55], v138 offset:9312
	s_waitcnt lgkmcnt(0)
	v_mfma_f32_32x32x16_bf16 v[68:83], v[52:55], v[84:87], v[68:83]
	v_mfma_f32_32x32x16_bf16 v[52:67], v[110:113], v[96:99], v[2:17]
	ds_read_b128 v[110:113], v138 offset:13856
	s_waitcnt lgkmcnt(0)
	v_mfma_f32_32x32x16_bf16 v[52:67], v[110:113], v[92:95], v[52:67]
	ds_read_b128 v[110:113], v138 offset:13888
	s_waitcnt lgkmcnt(0)
	v_mfma_f32_32x32x16_bf16 v[52:67], v[110:113], v[88:91], v[52:67]
	ds_read_b128 v[110:113], v138 offset:13920
	s_waitcnt lgkmcnt(0)
	v_mfma_f32_32x32x16_bf16 v[52:67], v[110:113], v[84:87], v[52:67]
	s_setprio 0
	s_nop 0
	v_max3_f32 v182, v68, s24, v69
	v_max3_f32 v182, v182, v70, v71
	v_max3_f32 v182, v182, v72, v73
	v_max3_f32 v182, v182, v74, v75
	v_max3_f32 v182, v182, v76, v77
	v_max3_f32 v182, v182, v78, v79
	v_max3_f32 v182, v182, v80, v81
	v_max3_f32 v182, v182, v82, v83
	s_nop 1
	v_max3_f32 v182, v182, v52, v53
	v_max3_f32 v182, v182, v54, v55
	v_max3_f32 v182, v182, v56, v57
	v_max3_f32 v182, v182, v58, v59
	v_max3_f32 v182, v182, v60, v61
	v_max3_f32 v182, v182, v62, v63
	v_max3_f32 v182, v182, v64, v65
	v_max3_f32 v182, v182, v66, v67
	s_add_i32 s1, 0, 0x6c00
	v_mov_b32_e32 v184, v182
	s_cmp_lg_u32 s1, -1
	s_nop 0
	v_permlane32_swap_b32_e32 v182, v184
	s_cselect_b32 s1, s1, 0
	v_max_f32_e32 v184, v184, v184
	v_max_f32_e32 v182, v182, v182
	v_add_u32_e32 v51, s1, v108
	ds_read_b64_tr_b16 v[136:137], v51 offset:0
	ds_read_b64_tr_b16 v[138:139], v51 offset:1152
	ds_read_b64_tr_b16 v[132:133], v51 offset:64
	ds_read_b64_tr_b16 v[134:135], v51 offset:1216
	ds_read_b64_tr_b16 v[128:129], v51 offset:2304
	ds_read_b64_tr_b16 v[130:131], v51 offset:3456
	ds_read_b64_tr_b16 v[124:125], v51 offset:2368
	ds_read_b64_tr_b16 v[126:127], v51 offset:3520
	ds_read_b64_tr_b16 v[120:121], v51 offset:4608
	ds_read_b64_tr_b16 v[122:123], v51 offset:5760
	ds_read_b64_tr_b16 v[116:117], v51 offset:4672
	ds_read_b64_tr_b16 v[118:119], v51 offset:5824
	ds_read_b64_tr_b16 v[112:113], v51 offset:6912
	ds_read_b64_tr_b16 v[114:115], v51 offset:8064
	ds_read_b64_tr_b16 v[108:109], v51 offset:6976
	ds_read_b64_tr_b16 v[110:111], v51 offset:8128
	s_waitcnt lgkmcnt(0)
	v_max_f32_e32 v184, v182, v184
	v_sub_f32_e32 v182, v184, v185
	v_cmp_lt_f32_e32 vcc, s25, v182
	v_mov_b32_e32 v182, 1.0
	s_cbranch_vccz .LBB0_445
	v_max_f32_e32 v158, v184, v184
	v_max_f32_e32 v184, v185, v185
	v_max_f32_e32 v186, v184, v158
	v_sub_f32_e32 v158, v185, v186
	v_mul_f32_e32 v158, 0x3fb8aa3b, v158
	v_exp_f32_e32 v184, v158
	v_mul_f32_e32 v158, 0x3fb8aa3b, v186
	v_pk_mul_f32 v[48:49], v[48:49], v[184:185] op_sel_hi:[1,0]
	v_pk_mul_f32 v[46:47], v[46:47], v[184:185] op_sel_hi:[1,0]
	v_pk_mul_f32 v[44:45], v[44:45], v[184:185] op_sel_hi:[1,0]
	v_pk_mul_f32 v[42:43], v[42:43], v[184:185] op_sel_hi:[1,0]
	v_pk_mul_f32 v[40:41], v[40:41], v[184:185] op_sel_hi:[1,0]
	v_pk_mul_f32 v[38:39], v[38:39], v[184:185] op_sel_hi:[1,0]
	v_pk_mul_f32 v[36:37], v[36:37], v[184:185] op_sel_hi:[1,0]
	v_pk_mul_f32 v[34:35], v[34:35], v[184:185] op_sel_hi:[1,0]
	v_pk_mul_f32 v[32:33], v[32:33], v[184:185] op_sel_hi:[1,0]
	v_pk_mul_f32 v[30:31], v[30:31], v[184:185] op_sel_hi:[1,0]
	v_pk_mul_f32 v[28:29], v[28:29], v[184:185] op_sel_hi:[1,0]
	v_pk_mul_f32 v[26:27], v[26:27], v[184:185] op_sel_hi:[1,0]
	v_pk_mul_f32 v[24:25], v[24:25], v[184:185] op_sel_hi:[1,0]
	v_pk_mul_f32 v[22:23], v[22:23], v[184:185] op_sel_hi:[1,0]
	v_pk_mul_f32 v[20:21], v[20:21], v[184:185] op_sel_hi:[1,0]
	v_pk_mul_f32 v[18:19], v[18:19], v[184:185] op_sel_hi:[1,0]
	v_mov_b32_e32 v185, v186
	s_branch .LBB0_446

; template <int NB>
; DI void softmax_pv(f32x16 (&s)[2], float& mrun, float& lsum, f32x16 (&O)[2], unsigned vaddr) {
;     ...
;   float mx = -1e30f;
; #pragma unroll
;   for (int kb = 0; kb < NB; ++kb)
; #pragma unroll
;     for (int e = 0; e < 16; ++e) mx = fmaxf(mx, s[kb][e]);
; template <int kind>
; __device__ void attn_job(const Params& p, int layer, int idx, char* smem) {
;     ...
;   auto tile_row0 = [&](int i) { return (i < 4) ? (NLAT + b * CTXL + i * 64) : (lat0 + (i - 4) * 64); };
;   u32x4 kreg, vreg;
;   {
;     const size_t ro = (size_t)(tile_row0(0) + lkey) * ZW;
;     kreg = *(const u32x4*)(Z + ro + kcol + lc * 8);
;     vreg = *(const u32x4*)(Z + ro + vcol + lc * 8);
;   }
;   for (int i = 0; i < ntiles; ++i) {
;     u16* Kb = Ks + (i & 1) * 64 * KS_STRIDE;
;     u16* Vb = Vt + (i & 1) * 64 * KS_STRIDE;
;     *(u32x4*)(Kb + lkey * KS_STRIDE + lc * 8) = kreg;
;     *(u32x4*)(Vb + lkey * KS_STRIDE + lc * 8) = vreg;
;     lds_barrier();
;     if (i + 1 < ntiles) {
;       const size_t ro = (size_t)(tile_row0(i + 1) + lkey) * ZW;
;       kreg = *(const u32x4*)(Z + ro + kcol + lc * 8);
;       vreg = *(const u32x4*)(Z + ro + vcol + lc * 8);
;     }
;     if (kind == 1 && i >= 4) {
;       const int kr = R0 + i - 4;
;       if (kr >= r0A && kr < r0A + 9) {
;         f32x16 s[2];
; #pragma unroll
;         for (int st = 0; st < 4; ++st) s[0] = mfma32(ld_frag16(Kb + (k0 + tq) * KS_STRIDE + 16 * st + 8 * hh), qf[st], st == 0 ? zero16 : s[0]);
;         const bool rowvalid = (kr >= r0l) && (kr < r0l + 8);
;         const unsigned m = rowvalid ? colmask : 0u;
;         const float* brow = rpbs + (kr - qrow_l + 7) * 32 + dcbase;
; #pragma unroll
;         for (int e = 0; e < 16; ++e) {
;           const float bias = brow[(e & 3) + 8 * (e >> 2)];
;           s[0][e] = ((m >> e) & 1u) ? s[0][e] + bias : -1e30f;
;         }
;         softmax_pv<1>(s, mrun, lsum, O, (unsigned)(size_t)Vb + vlane_off + (unsigned)(k0 * KS_STRIDE * 2));
;       }
;     } else {
;       f32x16 s[2];
;       __builtin_amdgcn_s_setprio(1);
; #pragma unroll
;       for (int kb = 0; kb < 2; ++kb) {
; #pragma unroll
;         for (int st = 0; st < 4; ++st) s[kb] = mfma32(ld_frag16(Kb + (kb * 32 + tq) * KS_STRIDE + 16 * st + 8 * hh), qf[st], st == 0 ? zero16 : s[kb]);
;       }
;       __builtin_amdgcn_s_setprio(0);
;       softmax_pv<2>(s, mrun, lsum, O, (unsigned)(size_t)Vb + vlane_off);
.LBB0_452:
	s_and_b64 vcc, exec, s[0:1]
	s_cbranch_vccz .LBB0_455
	s_bfe_u32 s1, s18, 0x10001
	s_lshl_b32 s3, s1, 7
	s_lshl_b32 s1, s1, 6
	v_mov_b32_e32 v20, v234
	s_add_i32 s0, s18, 0xfffffb00
	s_or_b32 s4, s1, 0xa00
	s_or_b32 s5, s1, 0xa80
	s_lshl_b32 s2, s0, 6
	v_readfirstlane_b32 s1, v20
	s_lshl_b32 s0, s0, 7
	s_lshr_b32 s7, s1, 1
	s_and_b32 s0, s0, 0x80
	s_and_b32 s7, s7, 0x60
	s_and_b32 s2, s2, 0xf00
	s_or_b32 s0, s0, s7
	v_and_b32_e32 v157, 31, v20
	s_or_b32 s0, s0, s2
	v_or_b32_e32 v0, s0, v157
	v_or_b32_e32 v181, 0x8000, v0
	s_ashr_i32 s0, s1, 2
	s_andn2_b32 s0, s0, 63
	v_mul_u32_u24_e32 v0, 0xe00, v181
	s_add_i32 s0, s0, s3
	v_lshlrev_b32_e32 v0, 1, v0
	v_bfe_u32 v183, v20, 5, 1
	s_waitcnt vmcnt(11)
	v_lshl_add_u64 v[2:3], s[80:81], 0, v[0:1]
	s_ashr_i32 s1, s0, 31
	v_lshl_add_u64 v[2:3], s[0:1], 1, v[2:3]
	v_lshlrev_b32_e32 v26, 4, v183
	v_mov_b32_e32 v27, v1
	v_lshl_add_u64 v[2:3], v[2:3], 0, v[26:27]
	s_mov_b64 s[8:9], 0x1200
	s_movk_i32 s3, 0x1000
	v_lshl_add_u64 v[4:5], v[2:3], 0, s[8:9]
	v_add_co_u32_e32 v2, vcc, s3, v2
	s_waitcnt vmcnt(10)
	v_mov_b32_e32 v6, v1
	v_addc_co_u32_e32 v3, vcc, 0, v3, vcc
	global_load_dwordx4 v[96:99], v[2:3], off offset:512
	global_load_dwordx4 v[92:95], v[4:5], off offset:32
	global_load_dwordx4 v[88:91], v[4:5], off offset:64
	global_load_dwordx4 v[84:87], v[4:5], off offset:96
	v_mov_b32_e32 v2, v1
	v_mov_b32_e32 v3, v1
	v_mov_b32_e32 v4, v1
	v_mov_b32_e32 v5, v1
	v_mov_b32_e32 v7, v1
	v_mov_b32_e32 v8, v1
	v_mov_b32_e32 v9, v1
	v_mov_b32_e32 v10, v1
	v_mov_b32_e32 v11, v1
	v_mov_b32_e32 v12, v1
	v_mov_b32_e32 v13, v1
	v_mov_b32_e32 v14, v1
	v_mov_b32_e32 v15, v1
	v_mov_b32_e32 v0, v1
	v_mov_b64_e32 v[16:17], v[14:15]
	v_and_b32_e32 v18, 16, v20
	v_lshlrev_b32_e32 v19, 2, v20
	v_mov_b64_e32 v[14:15], v[12:13]
	v_mov_b64_e32 v[12:13], v[10:11]
	v_mov_b64_e32 v[10:11], v[8:9]
	v_mov_b64_e32 v[8:9], v[6:7]
	v_mov_b64_e32 v[6:7], v[4:5]
	v_mov_b64_e32 v[4:5], v[2:3]
	v_mov_b64_e32 v[2:3], v[0:1]
	v_ashrrev_i32_e32 v27, 3, v20
	v_bfe_u32 v0, v20, 2, 2
	v_and_or_b32 v18, v19, 12, v18
	v_lshl_or_b32 v0, v183, 2, v0
	v_lshlrev_b32_e32 v18, 1, v18
	s_movk_i32 s7, 0x90
	v_add_u32_e32 v109, s2, v27
	v_mad_u32_u24 v108, v0, s7, v18
	v_add_u32_e32 v216, 0x8000, v109
	v_mov_b64_e32 v[82:83], s[80:81]
	v_readlane_b32 s8, v254, 34
	v_lshlrev_b32_e32 v0, 3, v20
	v_mad_i64_i32 v[22:23], s[2:3], v216, s79, v[82:83]
	v_readlane_b32 s9, v254, 35
	s_lshl_b32 s8, s4, 1
	v_and_b32_e32 v0, 56, v0
	v_lshl_add_u64 v[18:19], v[22:23], 0, s[8:9]
	v_lshlrev_b32_e32 v0, 1, v0
	s_lshl_b32 s2, s5, 1
	s_mov_b32 s3, s9
	v_lshl_add_u64 v[18:19], v[18:19], 0, v[0:1]
	v_lshl_add_u64 v[22:23], v[22:23], 0, s[2:3]
	global_load_dwordx4 v[18:21], v[18:19], off
	v_lshl_add_u64 v[22:23], v[22:23], 0, v[0:1]
	global_load_dwordx4 v[22:25], v[22:23], off
	v_mul_lo_u32 v27, v27, s7
	v_add3_u32 v232, 0, v27, v0
	s_waitcnt vmcnt(1)
	ds_write_b128 v232, v[18:21]
	s_waitcnt vmcnt(0)
	ds_write_b128 v232, v[22:25] offset:18432
	v_add_u32_e32 v18, 0x8040, v109
	v_mad_i64_i32 v[18:19], s[4:5], v18, s79, v[82:83]
	v_lshl_add_u64 v[20:21], v[18:19], 0, s[8:9]
	v_lshl_add_u64 v[18:19], v[18:19], 0, s[2:3]
	s_waitcnt lgkmcnt(0)
	s_barrier
	v_lshl_add_u64 v[20:21], v[20:21], 0, v[0:1]
	v_lshl_add_u64 v[18:19], v[18:19], 0, v[0:1]
	global_load_dwordx4 v[100:103], v[20:21], off
	global_load_dwordx4 v[104:107], v[18:19], off
	s_setprio 1
	v_add_u32_e32 v217, 0, v26
	v_mad_u32_u24 v138, v157, s7, v217
	ds_read_b128 v[34:37], v138
	ds_read_b128 v[38:41], v138 offset:32
	s_waitcnt lgkmcnt(1)
	v_mfma_f32_32x32x16_bf16 v[18:33], v[34:37], v[96:99], v[2:17]
	ds_read_b128 v[34:37], v138 offset:64
	s_waitcnt lgkmcnt(1)
	v_mfma_f32_32x32x16_bf16 v[18:33], v[38:41], v[92:95], v[18:33]
	s_waitcnt lgkmcnt(0)
	v_mfma_f32_32x32x16_bf16 v[18:33], v[34:37], v[88:91], v[18:33]
	ds_read_b128 v[34:37], v138 offset:96
	s_waitcnt lgkmcnt(0)
	v_mfma_f32_32x32x16_bf16 v[18:33], v[34:37], v[84:87], v[18:33]
	ds_read_b128 v[34:37], v138 offset:4608
	s_waitcnt lgkmcnt(0)
	v_mfma_f32_32x32x16_bf16 v[66:81], v[34:37], v[96:99], v[2:17]
	ds_read_b128 v[34:37], v138 offset:4640
	s_waitcnt lgkmcnt(0)
	v_mfma_f32_32x32x16_bf16 v[66:81], v[34:37], v[92:95], v[66:81]
	ds_read_b128 v[34:37], v138 offset:4672
	s_waitcnt lgkmcnt(0)
	v_mfma_f32_32x32x16_bf16 v[66:81], v[34:37], v[88:91], v[66:81]
	ds_read_b128 v[34:37], v138 offset:4704
	s_waitcnt lgkmcnt(0)
	v_mfma_f32_32x32x16_bf16 v[66:81], v[34:37], v[84:87], v[66:81]
	s_setprio 0
	v_max3_f32 v34, v18, s24, v19
	v_max3_f32 v34, v34, v20, v21
	v_max3_f32 v34, v34, v22, v23
	v_max3_f32 v34, v34, v24, v25
	v_max3_f32 v34, v34, v26, v27
	v_max3_f32 v34, v34, v28, v29
	v_max3_f32 v34, v34, v30, v31
	v_max3_f32 v34, v34, v32, v33
	s_nop 2
	v_max3_f32 v34, v34, v66, v67
	v_max3_f32 v34, v34, v68, v69
	v_max3_f32 v34, v34, v70, v71
	v_max3_f32 v34, v34, v72, v73
	v_max3_f32 v34, v34, v74, v75
	v_max3_f32 v34, v34, v76, v77
	v_max3_f32 v34, v34, v78, v79
	v_max3_f32 v34, v34, v80, v81
	v_mov_b32_e32 v35, v34
	s_nop 1
	v_permlane32_swap_b32_e32 v34, v35
	v_max_f32_e32 v35, v35, v35
	v_max_f32_e32 v34, v34, v34
	v_max_f32_e32 v34, v34, v35
	s_add_i32 s4, 0, 0x4800
	v_max_f32_e32 v35, 0xf149f2ca, v34
	v_add_f32_e32 v34, 0x7149f2ca, v34
	s_cmp_lg_u32 s4, -1
	v_cmp_lt_f32_e32 vcc, s25, v34
	s_cselect_b32 s4, s4, 0
	s_cmp_eq_u64 vcc, 0
	s_cselect_b64 vcc, -1, 0
	v_cndmask_b32_e32 v233, v35, v240, vcc
	v_mul_f32_e32 v156, 0x3fb8aa3b, v233
	v_fma_f32 v18, v18, s28, -v156
	v_fma_f32 v19, v19, s28, -v156
	v_sub_f32_e32 v36, 0xf149f2ca, v35
	v_exp_f32_e32 v140, v18
	v_exp_f32_e32 v141, v19
	v_fma_f32 v18, v20, s28, -v156
	v_fma_f32 v19, v21, s28, -v156
	v_mul_f32_e32 v36, 0x3fb8aa3b, v36
	v_exp_f32_e32 v142, v18
	v_exp_f32_e32 v143, v19
	v_fma_f32 v18, v22, s28, -v156
	v_fma_f32 v19, v23, s28, -v156
	v_exp_f32_e32 v36, v36
	v_exp_f32_e32 v144, v18
	v_exp_f32_e32 v145, v19
	v_fma_f32 v18, v24, s28, -v156
	v_fma_f32 v19, v25, s28, -v156
	v_add_u32_e32 v218, s4, v108
	v_exp_f32_e32 v146, v18
	v_exp_f32_e32 v147, v19
	v_fma_f32 v18, v26, s28, -v156
	v_fma_f32 v19, v27, s28, -v156
	ds_read_b64_tr_b16 v[158:159], v218 offset:0
	ds_read_b64_tr_b16 v[160:161], v218 offset:1152
	ds_read_b64_tr_b16 v[134:135], v218 offset:64
	ds_read_b64_tr_b16 v[136:137], v218 offset:1216
	ds_read_b64_tr_b16 v[130:131], v218 offset:2304
	ds_read_b64_tr_b16 v[132:133], v218 offset:3456
	ds_read_b64_tr_b16 v[126:127], v218 offset:2368
	ds_read_b64_tr_b16 v[128:129], v218 offset:3520
	ds_read_b64_tr_b16 v[122:123], v218 offset:4608
	ds_read_b64_tr_b16 v[124:125], v218 offset:5760
	ds_read_b64_tr_b16 v[118:119], v218 offset:4672
	ds_read_b64_tr_b16 v[120:121], v218 offset:5824
	ds_read_b64_tr_b16 v[114:115], v218 offset:6912
	ds_read_b64_tr_b16 v[116:117], v218 offset:8064
	ds_read_b64_tr_b16 v[110:111], v218 offset:6976
	ds_read_b64_tr_b16 v[112:113], v218 offset:8128
	s_waitcnt lgkmcnt(0)
; DI f32x16 mfma32(bf16x8 a, bf16x8 b, f32x16 c) { return __builtin_amdgcn_mfma_f32_32x32x16_bf16(a, b, c, 0, 0, 0); }
; template <int NB>
; DI void softmax_pv(f32x16 (&s)[2], float& mrun, float& lsum, f32x16 (&O)[2], unsigned vaddr) {
;     ...
;   if (NB == 2) {
; #pragma unroll
;     for (int kb = 0; kb < 2; ++kb) {
; #pragma unroll
;       for (int e = 0; e < 16; e += 2) {
;         f32x2 t = {s[kb][e], s[kb][e + 1]};
;         t = t * l2e2 - mb2;
;         f32x2 pv;
;         pv[0] = __builtin_amdgcn_exp2f(t[0]);
;         pv[1] = __builtin_amdgcn_exp2f(t[1]);
;         s[kb][e] = pv[0];
;         s[kb][e + 1] = pv[1];
;         ps2 += pv;
;       }
;       u32x4 pp[2];
; #pragma unroll
;       for (int st = 0; st < 2; ++st)
; #pragma unroll
;         for (int j = 0; j < 4; ++j) pp[st][j] = pk_bf16(s[kb][8 * st + 2 * j], s[kb][8 * st + 2 * j + 1]);
;       __builtin_amdgcn_sched_barrier(0);
;       __builtin_amdgcn_s_setprio(1);
; #pragma unroll
;       for (int st = 0; st < 2; ++st) {
;         const bf16x8 pf = as_bf16x8(pp[st]);
; #pragma unroll
;         for (int db = 0; db < 2; ++db) {
;           const int ix = ((kb * 2 + st) * 2 + db) * 2;
;           u32x4 av;
;           av[0] = vf[ix][0]; av[1] = vf[ix][1]; av[2] = vf[ix + 1][0]; av[3] = vf[ix + 1][1];
;           O[db] = mfma32(as_bf16x8(av), pf, O[db]);
;         }
;       }
;       __builtin_amdgcn_s_setprio(0);
;       __builtin_amdgcn_sched_barrier(0);
;     }
	v_mul_f32_e32 v34, 0, v36
	v_exp_f32_e32 v148, v18
	v_exp_f32_e32 v149, v19
	v_fma_f32 v18, v28, s28, -v156
	v_fma_f32 v19, v29, s28, -v156
	v_cndmask_b32_e64 v50, v34, 0, vcc
	v_exp_f32_e32 v150, v18
	v_exp_f32_e32 v151, v19
	v_fma_f32 v18, v30, s28, -v156
	v_fma_f32 v19, v31, s28, -v156
	v_mov_b32_e32 v51, v50
	v_exp_f32_e32 v152, v18
	v_exp_f32_e32 v153, v19
	v_fma_f32 v18, v32, s28, -v156
	v_fma_f32 v19, v33, s28, -v156
	v_mov_b32_e32 v52, v50
	v_exp_f32_e32 v154, v18
	v_exp_f32_e32 v155, v19
	v_mov_b32_e32 v53, v50
	v_mov_b32_e32 v54, v50
	v_mov_b32_e32 v55, v50
	v_mov_b32_e32 v56, v50
	v_mov_b32_e32 v57, v50
	v_mov_b32_e32 v58, v50
	v_mov_b32_e32 v59, v50
	v_mov_b32_e32 v60, v50
	v_mov_b32_e32 v61, v50
	v_mov_b32_e32 v62, v50
	v_mov_b32_e32 v63, v50
	v_mov_b32_e32 v64, v50
	v_mov_b32_e32 v65, v50
	v_cvt_pk_bf16_f32 v162, v140, v141
	v_cvt_pk_bf16_f32 v163, v142, v143
	v_cvt_pk_bf16_f32 v164, v144, v145
	v_cvt_pk_bf16_f32 v165, v146, v147
	v_cvt_pk_bf16_f32 v166, v148, v149
	v_cvt_pk_bf16_f32 v167, v150, v151
	v_cvt_pk_bf16_f32 v168, v152, v153
	v_cvt_pk_bf16_f32 v169, v154, v155
	s_setprio 1
	v_mov_b64_e32 v[18:19], v[50:51]
	v_mov_b64_e32 v[20:21], v[52:53]
	v_mov_b64_e32 v[22:23], v[54:55]
	v_mov_b64_e32 v[24:25], v[56:57]
	v_mov_b64_e32 v[26:27], v[58:59]
	v_mov_b64_e32 v[28:29], v[60:61]
	v_mov_b64_e32 v[30:31], v[62:63]
	v_mov_b64_e32 v[32:33], v[64:65]
	v_mfma_f32_32x32x16_bf16 v[34:49], v[158:161], v[162:165], v[50:65]
	s_nop 0
	v_mfma_f32_32x32x16_bf16 v[18:33], v[134:137], v[162:165], v[18:33]
	v_mfma_f32_32x32x16_bf16 v[34:49], v[130:133], v[166:169], v[34:49]
	v_mfma_f32_32x32x16_bf16 v[18:33], v[126:129], v[166:169], v[18:33]
	s_setprio 0
	s_nop 1
	v_fma_f32 v52, v66, s28, -v156
	v_fma_f32 v53, v67, s28, -v156
	v_exp_f32_e32 v158, v52
	v_exp_f32_e32 v159, v53
	v_fma_f32 v52, v68, s28, -v156
	v_fma_f32 v53, v69, s28, -v156
	s_nop 0
	v_exp_f32_e32 v160, v52
	v_exp_f32_e32 v161, v53
	v_fma_f32 v52, v70, s28, -v156
	v_fma_f32 v53, v71, s28, -v156
	s_nop 0
	v_exp_f32_e32 v162, v52
	v_exp_f32_e32 v163, v53
	v_fma_f32 v52, v72, s28, -v156
	v_fma_f32 v53, v73, s28, -v156
	v_cvt_pk_bf16_f32 v54, v162, v163
	v_exp_f32_e32 v164, v52
	v_exp_f32_e32 v165, v53
	v_fma_f32 v52, v74, s28, -v156
	v_fma_f32 v53, v75, s28, -v156
	v_cvt_pk_bf16_f32 v55, v164, v165
	v_exp_f32_e32 v166, v52
	v_exp_f32_e32 v167, v53
	v_fma_f32 v52, v76, s28, -v156
	v_fma_f32 v53, v77, s28, -v156
	v_cvt_pk_bf16_f32 v56, v166, v167
	v_exp_f32_e32 v168, v52
	v_exp_f32_e32 v169, v53
	v_fma_f32 v52, v78, s28, -v156
	v_fma_f32 v53, v79, s28, -v156
	v_cvt_pk_bf16_f32 v57, v168, v169
	v_exp_f32_e32 v170, v52
	v_exp_f32_e32 v171, v53
	v_fma_f32 v52, v80, s28, -v156
	v_fma_f32 v53, v81, s28, -v156
	v_cvt_pk_bf16_f32 v58, v170, v171
	v_exp_f32_e32 v178, v52
	v_exp_f32_e32 v179, v53
	v_cvt_pk_bf16_f32 v52, v158, v159
	v_cvt_pk_bf16_f32 v53, v160, v161
	v_cvt_pk_bf16_f32 v59, v178, v179
	s_setprio 1
	v_mfma_f32_32x32x16_bf16 v[34:49], v[122:125], v[52:55], v[34:49]
	v_mfma_f32_32x32x16_bf16 v[18:33], v[118:121], v[52:55], v[18:33]
	v_mfma_f32_32x32x16_bf16 v[34:49], v[114:117], v[56:59], v[34:49]
	v_mfma_f32_32x32x16_bf16 v[18:33], v[110:113], v[56:59], v[18:33]
	s_setprio 0
	v_add_u32_e32 v51, 0x8080, v109
	v_mad_i64_i32 v[52:53], s[4:5], v51, s79, v[82:83]
	s_waitcnt vmcnt(1)
	ds_write_b128 v232, v[100:103] offset:9216
	s_waitcnt vmcnt(0)
	ds_write_b128 v232, v[104:107] offset:27648
	v_writelane_b32 v254, s8, 34
	s_waitcnt lgkmcnt(0)
	s_barrier
; template <int NB>
; DI void softmax_pv(f32x16 (&s)[2], float& mrun, float& lsum, f32x16 (&O)[2], unsigned vaddr) {
;     ...
;   float mx = -1e30f;
; #pragma unroll
;   for (int kb = 0; kb < NB; ++kb)
; #pragma unroll
;     for (int e = 0; e < 16; ++e) mx = fmaxf(mx, s[kb][e]);
;   mx = xmax32(mx);
;   constexpr float THR = 8.f;
;   float alpha = 1.f;
;   if (__builtin_amdgcn_ballot_w64(mx - mrun > THR) != 0ull) {
;     const float mnew = fmaxf(mrun, mx);
;     alpha = __builtin_amdgcn_exp2f((mrun - mnew) * L2E);
;     mrun = mnew;
; #pragma unroll
; template <int kind>
; __device__ void attn_job(const Params& p, int layer, int idx, char* smem) {
;     ...
;   for (int i = 0; i < ntiles; ++i) {
;     u16* Kb = Ks + (i & 1) * 64 * KS_STRIDE;
;     u16* Vb = Vt + (i & 1) * 64 * KS_STRIDE;
;     *(u32x4*)(Kb + lkey * KS_STRIDE + lc * 8) = kreg;
;     *(u32x4*)(Vb + lkey * KS_STRIDE + lc * 8) = vreg;
;     lds_barrier();
;     if (i + 1 < ntiles) {
;       const size_t ro = (size_t)(tile_row0(i + 1) + lkey) * ZW;
;       kreg = *(const u32x4*)(Z + ro + kcol + lc * 8);
;       vreg = *(const u32x4*)(Z + ro + vcol + lc * 8);
;     }
;     if (kind == 1 && i >= 4) {
;       const int kr = R0 + i - 4;
;       if (kr >= r0A && kr < r0A + 9) {
;         f32x16 s[2];
; #pragma unroll
;         for (int st = 0; st < 4; ++st) s[0] = mfma32(ld_frag16(Kb + (k0 + tq) * KS_STRIDE + 16 * st + 8 * hh), qf[st], st == 0 ? zero16 : s[0]);
;         const bool rowvalid = (kr >= r0l) && (kr < r0l + 8);
;         const unsigned m = rowvalid ? colmask : 0u;
;         const float* brow = rpbs + (kr - qrow_l + 7) * 32 + dcbase;
; #pragma unroll
;         for (int e = 0; e < 16; ++e) {
;           const float bias = brow[(e & 3) + 8 * (e >> 2)];
;           s[0][e] = ((m >> e) & 1u) ? s[0][e] + bias : -1e30f;
;         }
;         softmax_pv<1>(s, mrun, lsum, O, (unsigned)(size_t)Vb + vlane_off + (unsigned)(k0 * KS_STRIDE * 2));
;       }
;     } else {
;       f32x16 s[2];
;       __builtin_amdgcn_s_setprio(1);
; #pragma unroll
;       for (int kb = 0; kb < 2; ++kb) {
; #pragma unroll
;         for (int st = 0; st < 4; ++st) s[kb] = mfma32(ld_frag16(Kb + (kb * 32 + tq) * KS_STRIDE + 16 * st + 8 * hh), qf[st], st == 0 ? zero16 : s[kb]);
;       }
;       __builtin_amdgcn_s_setprio(0);
;       softmax_pv<2>(s, mrun, lsum, O, (unsigned)(size_t)Vb + vlane_off);
	s_nop 0
	v_lshl_add_u64 v[54:55], v[52:53], 0, s[8:9]
	v_lshl_add_u64 v[54:55], v[54:55], 0, v[0:1]
	v_lshl_add_u64 v[52:53], v[52:53], 0, s[2:3]
	v_lshl_add_u64 v[52:53], v[52:53], 0, v[0:1]
	global_load_dwordx4 v[100:103], v[54:55], off
	global_load_dwordx4 v[104:107], v[52:53], off
	v_writelane_b32 v254, s9, 35
	s_setprio 1
	ds_read_b128 v[52:55], v138 offset:9216
	ds_read_b128 v[56:59], v138 offset:9248
	s_waitcnt lgkmcnt(1)
	v_mfma_f32_32x32x16_bf16 v[68:83], v[52:55], v[96:99], v[2:17]
	ds_read_b128 v[52:55], v138 offset:9280
	ds_read_b128 v[110:113], v138 offset:13824
	s_waitcnt lgkmcnt(2)
	v_mfma_f32_32x32x16_bf16 v[68:83], v[56:59], v[92:95], v[68:83]
	s_waitcnt lgkmcnt(1)
	v_mfma_f32_32x32x16_bf16 v[68:83], v[52:55], v[88:91], v[68:83]
	ds_read_b128 v[52:55], v138 offset:9312
	s_waitcnt lgkmcnt(0)
	v_mfma_f32_32x32x16_bf16 v[68:83], v[52:55], v[84:87], v[68:83]
	v_mfma_f32_32x32x16_bf16 v[52:67], v[110:113], v[96:99], v[2:17]
	ds_read_b128 v[110:113], v138 offset:13856
	s_waitcnt lgkmcnt(0)
	v_mfma_f32_32x32x16_bf16 v[52:67], v[110:113], v[92:95], v[52:67]
	ds_read_b128 v[110:113], v138 offset:13888
	s_waitcnt lgkmcnt(0)
	v_mfma_f32_32x32x16_bf16 v[52:67], v[110:113], v[88:91], v[52:67]
	ds_read_b128 v[110:113], v138 offset:13920
	s_waitcnt lgkmcnt(0)
	v_mfma_f32_32x32x16_bf16 v[52:67], v[110:113], v[84:87], v[52:67]
	s_setprio 0
	s_nop 0
	v_max3_f32 v180, v68, s24, v69
	v_max3_f32 v180, v180, v70, v71
	v_max3_f32 v180, v180, v72, v73
	v_max3_f32 v180, v180, v74, v75
	v_max3_f32 v180, v180, v76, v77
	v_max3_f32 v180, v180, v78, v79
	v_max3_f32 v180, v180, v80, v81
	v_max3_f32 v180, v180, v82, v83
	s_nop 1
	v_max3_f32 v180, v180, v52, v53
	v_max3_f32 v180, v180, v54, v55
	v_max3_f32 v180, v180, v56, v57
	v_max3_f32 v180, v180, v58, v59
	v_max3_f32 v180, v180, v60, v61
	v_max3_f32 v180, v180, v62, v63
	v_max3_f32 v180, v180, v64, v65
	v_max3_f32 v180, v180, v66, v67
	s_add_i32 s3, 0, 0x6c00
	v_mov_b32_e32 v182, v180
	s_cmp_lg_u32 s3, -1
	s_nop 0
	v_permlane32_swap_b32_e32 v180, v182
	s_cselect_b32 s3, s3, 0
	v_max_f32_e32 v182, v182, v182
	v_max_f32_e32 v180, v180, v180
	v_add_u32_e32 v51, s3, v108
	ds_read_b64_tr_b16 v[136:137], v51 offset:0
	ds_read_b64_tr_b16 v[138:139], v51 offset:1152
	ds_read_b64_tr_b16 v[132:133], v51 offset:64
	ds_read_b64_tr_b16 v[134:135], v51 offset:1216
	ds_read_b64_tr_b16 v[128:129], v51 offset:2304
	ds_read_b64_tr_b16 v[130:131], v51 offset:3456
	ds_read_b64_tr_b16 v[124:125], v51 offset:2368
	ds_read_b64_tr_b16 v[126:127], v51 offset:3520
	ds_read_b64_tr_b16 v[120:121], v51 offset:4608
	ds_read_b64_tr_b16 v[122:123], v51 offset:5760
	ds_read_b64_tr_b16 v[116:117], v51 offset:4672
	ds_read_b64_tr_b16 v[118:119], v51 offset:5824
	ds_read_b64_tr_b16 v[112:113], v51 offset:6912
	ds_read_b64_tr_b16 v[114:115], v51 offset:8064
	ds_read_b64_tr_b16 v[108:109], v51 offset:6976
	ds_read_b64_tr_b16 v[110:111], v51 offset:8128
	s_waitcnt lgkmcnt(0)
	v_max_f32_e32 v182, v180, v182
	v_sub_f32_e32 v180, v182, v233
	v_cmp_lt_f32_e32 vcc, s25, v180
	v_mov_b32_e32 v180, 1.0
	s_cbranch_vccz .LBB0_781
	v_max_f32_e32 v156, v182, v182
	v_max_f32_e32 v182, v233, v233
	v_max_f32_e32 v184, v182, v156
	v_sub_f32_e32 v156, v233, v184
	v_mul_f32_e32 v156, 0x3fb8aa3b, v156
	v_exp_f32_e32 v182, v156
	v_mul_f32_e32 v156, 0x3fb8aa3b, v184
	v_mov_b32_e32 v233, v184
	v_pk_mul_f32 v[48:49], v[48:49], v[182:183] op_sel_hi:[1,0]
	v_pk_mul_f32 v[46:47], v[46:47], v[182:183] op_sel_hi:[1,0]
	v_pk_mul_f32 v[44:45], v[44:45], v[182:183] op_sel_hi:[1,0]
	v_pk_mul_f32 v[42:43], v[42:43], v[182:183] op_sel_hi:[1,0]
	v_pk_mul_f32 v[40:41], v[40:41], v[182:183] op_sel_hi:[1,0]
	v_pk_mul_f32 v[38:39], v[38:39], v[182:183] op_sel_hi:[1,0]
	v_pk_mul_f32 v[36:37], v[36:37], v[182:183] op_sel_hi:[1,0]
	v_pk_mul_f32 v[34:35], v[34:35], v[182:183] op_sel_hi:[1,0]
	v_pk_mul_f32 v[32:33], v[32:33], v[182:183] op_sel_hi:[1,0]
	v_pk_mul_f32 v[30:31], v[30:31], v[182:183] op_sel_hi:[1,0]
	v_pk_mul_f32 v[28:29], v[28:29], v[182:183] op_sel_hi:[1,0]
	v_pk_mul_f32 v[26:27], v[26:27], v[182:183] op_sel_hi:[1,0]
	v_pk_mul_f32 v[24:25], v[24:25], v[182:183] op_sel_hi:[1,0]
	v_pk_mul_f32 v[22:23], v[22:23], v[182:183] op_sel_hi:[1,0]
	v_pk_mul_f32 v[20:21], v[20:21], v[182:183] op_sel_hi:[1,0]
	v_pk_mul_f32 v[18:19], v[18:19], v[182:183] op_sel_hi:[1,0]
	s_branch .LBB0_782

; DI f32x16 mfma32(bf16x8 a, bf16x8 b, f32x16 c) { return __builtin_amdgcn_mfma_f32_32x32x16_bf16(a, b, c, 0, 0, 0); }
; template <int NB>
; DI void softmax_pv(f32x16 (&s)[2], float& mrun, float& lsum, f32x16 (&O)[2], unsigned vaddr) {
;     ...
;   if (NB == 2) {
; #pragma unroll
;     for (int kb = 0; kb < 2; ++kb) {
; #pragma unroll
;       for (int e = 0; e < 16; e += 2) {
;         f32x2 t = {s[kb][e], s[kb][e + 1]};
;         t = t * l2e2 - mb2;
;         f32x2 pv;
;         pv[0] = __builtin_amdgcn_exp2f(t[0]);
;         pv[1] = __builtin_amdgcn_exp2f(t[1]);
;         s[kb][e] = pv[0];
;         s[kb][e + 1] = pv[1];
;         ps2 += pv;
;       }
;       u32x4 pp[2];
; #pragma unroll
;       for (int st = 0; st < 2; ++st)
; #pragma unroll
;         for (int j = 0; j < 4; ++j) pp[st][j] = pk_bf16(s[kb][8 * st + 2 * j], s[kb][8 * st + 2 * j + 1]);
;       __builtin_amdgcn_sched_barrier(0);
;       __builtin_amdgcn_s_setprio(1);
; #pragma unroll
;       for (int st = 0; st < 2; ++st) {
;         const bf16x8 pf = as_bf16x8(pp[st]);
; #pragma unroll
;         for (int db = 0; db < 2; ++db) {
;           const int ix = ((kb * 2 + st) * 2 + db) * 2;
;           u32x4 av;
;           av[0] = vf[ix][0]; av[1] = vf[ix][1]; av[2] = vf[ix + 1][0]; av[3] = vf[ix + 1][1];
;           O[db] = mfma32(as_bf16x8(av), pf, O[db]);
;         }
;       }
;       __builtin_amdgcn_s_setprio(0);
;       __builtin_amdgcn_sched_barrier(0);
;     }
;     ...
;   lsum = lsum * alpha + (ps2[0] + ps2[1]);
.LBB0_474:
	v_mul_f32_e32 v226, 0x3fb8aa3b, v224
	v_fma_f32 v112, v112, s28, -v226
	v_fma_f32 v113, v113, s28, -v226
	s_nop 0
	v_exp_f32_e32 v228, v112
	v_exp_f32_e32 v229, v113
	v_fma_f32 v112, v114, s28, -v226
	v_fma_f32 v113, v115, s28, -v226
	s_nop 0
	v_exp_f32_e32 v230, v112
	v_exp_f32_e32 v231, v113
	v_fma_f32 v112, v116, s28, -v226
	v_fma_f32 v113, v117, s28, -v226
	s_nop 0
	v_exp_f32_e32 v232, v112
	v_exp_f32_e32 v233, v113
	v_fma_f32 v112, v118, s28, -v226
	v_fma_f32 v113, v119, s28, -v226
	v_cvt_pk_bf16_f32 v114, v232, v233
	v_exp_f32_e32 v238, v112
	v_exp_f32_e32 v239, v113
	v_fma_f32 v112, v120, s28, -v226
	v_fma_f32 v113, v121, s28, -v226
	v_cvt_pk_bf16_f32 v115, v238, v239
	v_exp_f32_e32 v120, v112
	v_exp_f32_e32 v121, v113
	v_fma_f32 v112, v122, s28, -v226
	v_fma_f32 v113, v123, s28, -v226
	v_cvt_pk_bf16_f32 v116, v120, v121
	v_exp_f32_e32 v122, v112
	v_exp_f32_e32 v123, v113
	v_fma_f32 v112, v124, s28, -v226
	v_fma_f32 v113, v125, s28, -v226
	v_cvt_pk_bf16_f32 v117, v122, v123
	v_exp_f32_e32 v124, v112
	v_exp_f32_e32 v125, v113
	v_fma_f32 v112, v126, s28, -v226
	v_fma_f32 v113, v127, s28, -v226
	v_cvt_pk_bf16_f32 v118, v124, v125
	v_exp_f32_e32 v126, v112
	v_exp_f32_e32 v127, v113
	v_cvt_pk_bf16_f32 v112, v228, v229
	v_cvt_pk_bf16_f32 v113, v230, v231
	v_cvt_pk_bf16_f32 v119, v126, v127
	s_setprio 1
	v_mfma_f32_32x32x16_bf16 v[64:79], v[168:171], v[112:115], v[64:79]
	v_mfma_f32_32x32x16_bf16 v[80:95], v[164:167], v[112:115], v[80:95]
	v_add_f32_e64 v112, v228, 0
	v_add_f32_e64 v113, v229, 0
	v_add_f32_e64 v112, v230, v112
	v_add_f32_e64 v113, v231, v113
	v_add_f32_e64 v112, v232, v112
	v_add_f32_e64 v113, v233, v113
	v_pk_add_f32 v[112:113], v[238:239], v[112:113]
	v_mfma_f32_32x32x16_bf16 v[64:79], v[160:163], v[116:119], v[64:79]
	v_add_f32_e64 v112, v120, v112
	v_add_f32_e64 v113, v121, v113
	v_add_f32_e64 v112, v122, v112
	v_add_f32_e64 v113, v123, v113
	v_add_f32_e64 v112, v124, v112
	v_add_f32_e64 v113, v125, v113
	v_pk_add_f32 v[112:113], v[126:127], v[112:113]
	v_mfma_f32_32x32x16_bf16 v[80:95], v[156:159], v[116:119], v[80:95]
	s_setprio 0
	v_fma_f32 v96, v96, s28, -v226
	v_fma_f32 v97, v97, s28, -v226
	v_exp_f32_e32 v114, v96
	v_exp_f32_e32 v115, v97
	v_fma_f32 v96, v98, s28, -v226
	v_fma_f32 v97, v99, s28, -v226
	s_nop 0
	v_exp_f32_e32 v116, v96
	v_exp_f32_e32 v117, v97
	v_fma_f32 v96, v100, s28, -v226
	v_fma_f32 v97, v101, s28, -v226
	s_nop 0
	v_exp_f32_e32 v118, v96
	v_exp_f32_e32 v119, v97
	v_fma_f32 v96, v102, s28, -v226
	v_fma_f32 v97, v103, s28, -v226
	v_cvt_pk_bf16_f32 v98, v118, v119
	v_exp_f32_e32 v120, v96
	v_exp_f32_e32 v121, v97
	v_fma_f32 v96, v104, s28, -v226
	v_fma_f32 v97, v105, s28, -v226
	v_cvt_pk_bf16_f32 v99, v120, v121
	v_exp_f32_e32 v104, v96
	v_exp_f32_e32 v105, v97
	v_fma_f32 v96, v106, s28, -v226
	v_fma_f32 v97, v107, s28, -v226
	v_cvt_pk_bf16_f32 v100, v104, v105
	v_exp_f32_e32 v106, v96
	v_exp_f32_e32 v107, v97
	v_fma_f32 v96, v108, s28, -v226
	v_fma_f32 v97, v109, s28, -v226
	v_cvt_pk_bf16_f32 v101, v106, v107
	v_exp_f32_e32 v108, v96
	v_exp_f32_e32 v109, v97
	v_fma_f32 v96, v110, s28, -v226
	v_fma_f32 v97, v111, s28, -v226
	v_cvt_pk_bf16_f32 v102, v108, v109
	v_exp_f32_e32 v110, v96
	v_exp_f32_e32 v111, v97
	v_cvt_pk_bf16_f32 v96, v114, v115
	v_cvt_pk_bf16_f32 v97, v116, v117
	v_cvt_pk_bf16_f32 v103, v110, v111
	s_setprio 1
	v_mfma_f32_32x32x16_bf16 v[64:79], v[152:155], v[96:99], v[64:79]
	v_mfma_f32_32x32x16_bf16 v[80:95], v[10:13], v[96:99], v[80:95]
	v_mfma_f32_32x32x16_bf16 v[64:79], v[6:9], v[100:103], v[64:79]
	v_add_f32_e64 v6, v114, v112
	v_add_f32_e64 v7, v115, v113
	v_add_f32_e64 v6, v116, v6
	v_add_f32_e64 v7, v117, v7
	v_add_f32_e64 v6, v118, v6
	v_add_f32_e64 v7, v119, v7
	v_pk_add_f32 v[6:7], v[120:121], v[6:7]
	v_mfma_f32_32x32x16_bf16 v[80:95], v[2:5], v[100:103], v[80:95]
	v_add_f32_e64 v6, v104, v6
	v_add_f32_e64 v7, v105, v7
	v_add_f32_e64 v6, v106, v6
	v_add_f32_e64 v7, v107, v7
	v_add_f32_e64 v6, v108, v6
	v_add_f32_e64 v7, v109, v7
	v_pk_add_f32 v[6:7], v[110:111], v[6:7]
	s_setprio 0
	v_add_f32_e32 v2, v6, v7
	v_mov_b64_e32 v[126:127], v[78:79]
	s_nop 1
	v_mov_b64_e32 v[110:111], v[94:95]
	v_fmac_f32_e32 v2, v192, v0
	v_mov_b64_e32 v[124:125], v[76:77]
	v_mov_b64_e32 v[122:123], v[74:75]
	v_mov_b64_e32 v[120:121], v[72:73]
	v_mov_b64_e32 v[118:119], v[70:71]
	v_mov_b64_e32 v[116:117], v[68:69]
	v_mov_b64_e32 v[114:115], v[66:67]
	v_mov_b64_e32 v[112:113], v[64:65]
	v_mov_b64_e32 v[108:109], v[92:93]
	v_mov_b64_e32 v[106:107], v[90:91]
	v_mov_b64_e32 v[104:105], v[88:89]
	v_mov_b64_e32 v[102:103], v[86:87]
	v_mov_b64_e32 v[100:101], v[84:85]
	v_mov_b64_e32 v[98:99], v[82:83]
	v_mov_b64_e32 v[96:97], v[80:81]
	s_branch .LBB0_513

; DI f32x16 mfma32(bf16x8 a, bf16x8 b, f32x16 c) { return __builtin_amdgcn_mfma_f32_32x32x16_bf16(a, b, c, 0, 0, 0); }
; template <int NB>
; DI void softmax_pv(f32x16 (&s)[2], float& mrun, float& lsum, f32x16 (&O)[2], unsigned vaddr) {
;     ...
;   } else {
; #pragma unroll
;     for (int e = 0; e < 16; e += 2) {
;       f32x2 t = {s[0][e], s[0][e + 1]};
;       t = t * l2e2 - mb2;
;       f32x2 pv;
;       pv[0] = __builtin_amdgcn_exp2f(t[0]);
;       pv[1] = __builtin_amdgcn_exp2f(t[1]);
;       s[0][e] = pv[0];
;       s[0][e + 1] = pv[1];
;       ps2 += pv;
;     }
;     __builtin_amdgcn_s_setprio(1);
; #pragma unroll
;     for (int st = 0; st < 2; ++st) {
;       u32x4 pp;
; #pragma unroll
;       for (int j = 0; j < 4; ++j) pp[j] = pk_bf16(s[0][8 * st + 2 * j], s[0][8 * st + 2 * j + 1]);
;       const bf16x8 pf = as_bf16x8(pp);
; #pragma unroll
;       for (int db = 0; db < 2; ++db) {
;         const int ix = (st * 2 + db) * 2;
;         u32x4 av;
;         av[0] = vf8[ix][0]; av[1] = vf8[ix][1]; av[2] = vf8[ix + 1][0]; av[3] = vf8[ix + 1][1];
;         O[db] = mfma32(as_bf16x8(av), pf, O[db]);
;       }
;     }
;     __builtin_amdgcn_s_setprio(0);
;   }
;   lsum = lsum * alpha + (ps2[0] + ps2[1]);
.LBB0_511:
	v_mul_f32_e32 v78, 0x3fb8aa3b, v193
	v_fma_f32 v14, v14, s28, -v78
	v_fma_f32 v15, v15, s28, -v78
	v_fma_f32 v68, v68, s28, -v78
	v_fma_f32 v69, v69, s28, -v78
	v_exp_f32_e32 v14, v14
	v_exp_f32_e32 v15, v15
	v_exp_f32_e32 v84, v68
	v_exp_f32_e32 v85, v69
	v_fma_f32 v68, v70, s28, -v78
	v_fma_f32 v69, v71, s28, -v78
	v_fma_f32 v80, v80, s28, -v78
	v_fma_f32 v81, v81, s28, -v78
	v_exp_f32_e32 v86, v68
	v_exp_f32_e32 v87, v69
	v_fma_f32 v68, v72, s28, -v78
	v_fma_f32 v69, v73, s28, -v78
	v_fma_f32 v82, v82, s28, -v78
	v_fma_f32 v83, v83, s28, -v78
	v_exp_f32_e32 v72, v68
	v_exp_f32_e32 v73, v69
	v_fma_f32 v68, v74, s28, -v78
	v_fma_f32 v69, v75, s28, -v78
	v_exp_f32_e32 v80, v80
	v_exp_f32_e32 v74, v68
	v_exp_f32_e32 v75, v69
	v_fma_f32 v68, v76, s28, -v78
	v_fma_f32 v69, v77, s28, -v78
	v_exp_f32_e32 v81, v81
	v_exp_f32_e32 v82, v82
	v_exp_f32_e32 v83, v83
	v_exp_f32_e32 v76, v68
	v_exp_f32_e32 v77, v69
	s_setprio 1
	v_cvt_pk_bf16_f32 v68, v14, v15
	v_cvt_pk_bf16_f32 v69, v80, v81
	v_cvt_pk_bf16_f32 v70, v82, v83
	v_cvt_pk_bf16_f32 v71, v84, v85
	s_nop 1
	v_mfma_f32_32x32x16_bf16 v[32:47], v[64:67], v[68:71], v[32:47]
	v_mfma_f32_32x32x16_bf16 v[48:63], v[10:13], v[68:71], v[48:63]
	v_cvt_pk_bf16_f32 v10, v86, v87
	v_cvt_pk_bf16_f32 v11, v72, v73
	v_cvt_pk_bf16_f32 v12, v74, v75
	v_cvt_pk_bf16_f32 v13, v76, v77
	s_nop 1
	v_mfma_f32_32x32x16_bf16 v[32:47], v[6:9], v[10:13], v[32:47]
	v_add_f32_e64 v6, v14, 0
	v_add_f32_e64 v7, v15, 0
	v_add_f32_e64 v6, v80, v6
	v_add_f32_e64 v7, v81, v7
	v_add_f32_e64 v6, v82, v6
	v_add_f32_e64 v7, v83, v7
	v_pk_add_f32 v[6:7], v[84:85], v[6:7]
	v_mfma_f32_32x32x16_bf16 v[48:63], v[2:5], v[10:13], v[48:63]
	v_add_f32_e64 v6, v86, v6
	v_add_f32_e64 v7, v87, v7
	v_add_f32_e64 v6, v72, v6
	v_add_f32_e64 v7, v73, v7
	v_add_f32_e64 v6, v74, v6
	v_add_f32_e64 v7, v75, v7
	v_pk_add_f32 v[6:7], v[76:77], v[6:7]
	s_setprio 0
	v_add_f32_e32 v2, v6, v7
	v_fmac_f32_e32 v2, v192, v0
	v_mov_b32_e32 v223, v47
	v_mov_b32_e32 v222, v46
	v_mov_b32_e32 v221, v45
	v_mov_b32_e32 v220, v44
	v_mov_b32_e32 v219, v43
	v_mov_b32_e32 v218, v42
	v_mov_b32_e32 v217, v41
	v_mov_b32_e32 v216, v40
	v_mov_b32_e32 v215, v39
	v_mov_b32_e32 v214, v38
	v_mov_b32_e32 v213, v37
	v_mov_b32_e32 v212, v36
	v_mov_b32_e32 v211, v35
	v_mov_b32_e32 v210, v34
	v_mov_b32_e32 v209, v33
	v_mov_b32_e32 v208, v32
	v_mov_b32_e32 v207, v63
	v_mov_b32_e32 v206, v62
	v_mov_b32_e32 v205, v61
	v_mov_b32_e32 v204, v60
	v_mov_b32_e32 v203, v59
	v_mov_b32_e32 v202, v58
	v_mov_b32_e32 v201, v57
	v_mov_b32_e32 v200, v56
	v_mov_b32_e32 v199, v55
	v_mov_b32_e32 v198, v54
	v_mov_b32_e32 v197, v53
	v_mov_b32_e32 v196, v52
	v_mov_b32_e32 v195, v51
	v_mov_b32_e32 v194, v50
	v_mov_b32_e32 v15, v49
	v_mov_b32_e32 v14, v48
	v_mov_b32_e32 v192, v2

; DI f32x16 mfma32(bf16x8 a, bf16x8 b, f32x16 c) { return __builtin_amdgcn_mfma_f32_32x32x16_bf16(a, b, c, 0, 0, 0); }
; template <int NB>
; DI void softmax_pv(f32x16 (&s)[2], float& mrun, float& lsum, f32x16 (&O)[2], unsigned vaddr) {
;     ...
;   if (NB == 2) {
; #pragma unroll
;     for (int kb = 0; kb < 2; ++kb) {
; #pragma unroll
;       for (int e = 0; e < 16; e += 2) {
;         f32x2 t = {s[kb][e], s[kb][e + 1]};
;         t = t * l2e2 - mb2;
;         f32x2 pv;
;         pv[0] = __builtin_amdgcn_exp2f(t[0]);
;         pv[1] = __builtin_amdgcn_exp2f(t[1]);
;         s[kb][e] = pv[0];
;         s[kb][e + 1] = pv[1];
;         ps2 += pv;
;       }
;       u32x4 pp[2];
; #pragma unroll
;       for (int st = 0; st < 2; ++st)
; #pragma unroll
;         for (int j = 0; j < 4; ++j) pp[st][j] = pk_bf16(s[kb][8 * st + 2 * j], s[kb][8 * st + 2 * j + 1]);
;       __builtin_amdgcn_sched_barrier(0);
;       __builtin_amdgcn_s_setprio(1);
; #pragma unroll
;       for (int st = 0; st < 2; ++st) {
;         const bf16x8 pf = as_bf16x8(pp[st]);
; #pragma unroll
;         for (int db = 0; db < 2; ++db) {
;           const int ix = ((kb * 2 + st) * 2 + db) * 2;
;           u32x4 av;
;           av[0] = vf[ix][0]; av[1] = vf[ix][1]; av[2] = vf[ix + 1][0]; av[3] = vf[ix + 1][1];
;           O[db] = mfma32(as_bf16x8(av), pf, O[db]);
;         }
;       }
;       __builtin_amdgcn_s_setprio(0);
;       __builtin_amdgcn_sched_barrier(0);
;     }
;     ...
;   lsum = lsum * alpha + (ps2[0] + ps2[1]);
.LBB0_523:
	v_mul_f32_e32 v144, 0x3fb8aa3b, v145
	v_fma_f32 v66, v66, s28, -v144
	v_fma_f32 v67, v67, s28, -v144
	s_add_i32 s7, s7, 1
	v_exp_f32_e32 v150, v66
	v_exp_f32_e32 v151, v67
	v_fma_f32 v66, v68, s28, -v144
	v_fma_f32 v67, v69, s28, -v144
	s_nop 0
	v_exp_f32_e32 v152, v66
	v_exp_f32_e32 v153, v67
	v_fma_f32 v66, v70, s28, -v144
	v_fma_f32 v67, v71, s28, -v144
	s_nop 0
	v_exp_f32_e32 v154, v66
	v_exp_f32_e32 v155, v67
	v_fma_f32 v66, v72, s28, -v144
	v_fma_f32 v67, v73, s28, -v144
	v_cvt_pk_bf16_f32 v68, v154, v155
	v_exp_f32_e32 v156, v66
	v_exp_f32_e32 v157, v67
	v_fma_f32 v66, v74, s28, -v144
	v_fma_f32 v67, v75, s28, -v144
	v_cvt_pk_bf16_f32 v69, v156, v157
	v_exp_f32_e32 v74, v66
	v_exp_f32_e32 v75, v67
	v_fma_f32 v66, v76, s28, -v144
	v_fma_f32 v67, v77, s28, -v144
	v_cvt_pk_bf16_f32 v70, v74, v75
	v_exp_f32_e32 v76, v66
	v_exp_f32_e32 v77, v67
	v_fma_f32 v66, v78, s28, -v144
	v_fma_f32 v67, v79, s28, -v144
	v_cvt_pk_bf16_f32 v71, v76, v77
	v_exp_f32_e32 v78, v66
	v_exp_f32_e32 v79, v67
	v_fma_f32 v66, v80, s28, -v144
	v_fma_f32 v67, v81, s28, -v144
	v_cvt_pk_bf16_f32 v72, v78, v79
	v_exp_f32_e32 v80, v66
	v_exp_f32_e32 v81, v67
	v_cvt_pk_bf16_f32 v66, v150, v151
	v_cvt_pk_bf16_f32 v67, v152, v153
	v_cvt_pk_bf16_f32 v73, v80, v81
	s_waitcnt lgkmcnt(0)
	s_setprio 1
	v_mfma_f32_32x32x16_bf16 v[18:33], v[134:137], v[66:69], v[18:33]
	v_mfma_f32_32x32x16_bf16 v[2:17], v[130:133], v[66:69], v[2:17]
	v_add_f32_e64 v66, v150, 0
	v_add_f32_e64 v67, v151, 0
	v_add_f32_e64 v66, v152, v66
	v_add_f32_e64 v67, v153, v67
	v_add_f32_e64 v66, v154, v66
	v_add_f32_e64 v67, v155, v67
	v_pk_add_f32 v[66:67], v[156:157], v[66:67]
	v_mfma_f32_32x32x16_bf16 v[18:33], v[126:129], v[70:73], v[18:33]
	v_add_f32_e64 v66, v74, v66
	v_add_f32_e64 v67, v75, v67
	v_add_f32_e64 v66, v76, v66
	v_add_f32_e64 v67, v77, v67
	v_add_f32_e64 v66, v78, v66
	v_add_f32_e64 v67, v79, v67
	v_pk_add_f32 v[66:67], v[80:81], v[66:67]
	v_mfma_f32_32x32x16_bf16 v[2:17], v[122:125], v[70:73], v[2:17]
	s_setprio 0
	v_fma_f32 v50, v50, s28, -v144
	v_fma_f32 v51, v51, s28, -v144
	v_exp_f32_e32 v68, v50
	v_exp_f32_e32 v69, v51
	v_fma_f32 v50, v52, s28, -v144
	v_fma_f32 v51, v53, s28, -v144
	s_nop 0
	v_exp_f32_e32 v70, v50
	v_exp_f32_e32 v71, v51
	v_fma_f32 v50, v54, s28, -v144
	v_fma_f32 v51, v55, s28, -v144
	s_nop 0
	v_exp_f32_e32 v72, v50
	v_exp_f32_e32 v73, v51
	v_fma_f32 v50, v56, s28, -v144
	v_fma_f32 v51, v57, s28, -v144
	v_cvt_pk_bf16_f32 v52, v72, v73
	v_exp_f32_e32 v74, v50
	v_exp_f32_e32 v75, v51
	v_fma_f32 v50, v58, s28, -v144
	v_fma_f32 v51, v59, s28, -v144
	v_cvt_pk_bf16_f32 v53, v74, v75
	v_exp_f32_e32 v58, v50
	v_exp_f32_e32 v59, v51
	v_fma_f32 v50, v60, s28, -v144
	v_fma_f32 v51, v61, s28, -v144
	v_cvt_pk_bf16_f32 v54, v58, v59
	v_exp_f32_e32 v60, v50
	v_exp_f32_e32 v61, v51
	v_fma_f32 v50, v62, s28, -v144
	v_fma_f32 v51, v63, s28, -v144
	v_cvt_pk_bf16_f32 v55, v60, v61
	v_exp_f32_e32 v62, v50
	v_exp_f32_e32 v63, v51
	v_fma_f32 v50, v64, s28, -v144
	v_fma_f32 v51, v65, s28, -v144
	v_cvt_pk_bf16_f32 v56, v62, v63
	v_exp_f32_e32 v64, v50
	v_exp_f32_e32 v65, v51
	v_cvt_pk_bf16_f32 v50, v68, v69
	v_cvt_pk_bf16_f32 v51, v70, v71
	v_cvt_pk_bf16_f32 v57, v64, v65
	s_setprio 1
	v_mfma_f32_32x32x16_bf16 v[18:33], v[118:121], v[50:53], v[18:33]
	v_mfma_f32_32x32x16_bf16 v[2:17], v[114:117], v[50:53], v[2:17]
	v_add_f32_e64 v50, v68, v66
	v_add_f32_e64 v51, v69, v67
	v_add_f32_e64 v50, v70, v50
	v_add_f32_e64 v51, v71, v51
	v_add_f32_e64 v50, v72, v50
	v_add_f32_e64 v51, v73, v51
	v_pk_add_f32 v[50:51], v[74:75], v[50:51]
	v_mfma_f32_32x32x16_bf16 v[18:33], v[110:113], v[54:57], v[18:33]
	v_add_f32_e64 v50, v58, v50
	v_add_f32_e64 v51, v59, v51
	v_add_f32_e64 v50, v60, v50
	v_add_f32_e64 v51, v61, v51
	v_add_f32_e64 v50, v62, v50
	v_add_f32_e64 v51, v63, v51
	v_pk_add_f32 v[50:51], v[64:65], v[50:51]
	v_mfma_f32_32x32x16_bf16 v[2:17], v[106:109], v[54:57], v[2:17]
	s_setprio 0
	v_add_f32_e32 v106, v50, v51
	s_add_i32 s6, s6, 64
	s_cmp_eq_u32 s7, 35
	v_fmac_f32_e32 v106, v149, v146
	s_cbranch_scc1 .LBB0_525
	v_mov_b32_e32 v149, v106
	s_branch .LBB0_520
